# MoBA prep loop: gain pointer hoisted, q/k row loads issued with the V loads, gain loads before the transpose barrier
# speedup vs baseline: 1.0016x; 1.0016x over previous
.Lmp_entry:
	v_lshrrev_b32_e32 v140, 1, v1
	v_and_b32_e32 v4, 24, v1
	v_lshrrev_b32_e32 v5, 3, v1
	v_lshlrev_b32_e32 v2, 5, v1
	v_and_b32_e32 v3, 0x1e0, v140
	v_and_b32_e32 v5, 4, v5
	v_and_or_b32 v4, v140, 3, v4
	v_and_b32_e32 v2, 32, v2
	v_or3_b32 v3, v4, v5, v3
	v_mul_u32_u24_e32 v4, 0x210, v2
	s_add_i32 s0, 0, 0x10400
	v_lshlrev_b32_e32 v3, 1, v3
	v_add3_u32 v141, s0, v4, v3
	s_movk_i32 s1, 0xff
	v_and_b32_e32 v4, 63, v1
	v_cmp_lt_u32_e64 s[2:3], s1, v1
	s_movk_i32 s1, 0x104
	v_and_b32_e32 v5, 0xc0, v1
	v_lshl_add_u32 v7, v4, 2, 0
	v_mad_u32_u24 v142, v5, s1, v7
	v_lshlrev_b32_e32 v5, 4, v1
	v_and_b32_e32 v98, 0x1f0, v5
	v_add_u32_e32 v11, s0, v98
	s_load_dword s0, s[16:17], 0x10
	s_movk_i32 s4, 0x100
	v_and_b32_e32 v3, 0x300, v1
	v_readlane_b32 s8, v246, 0
	v_cmp_gt_u32_e32 vcc, s4, v1
	v_cmp_eq_u32_e64 s[4:5], s4, v3
	v_mul_u32_u24_sdwa v3, v1, s1 dst_sel:DWORD dst_unused:UNUSED_PAD src0_sel:BYTE_0 src1_sel:DWORD
	s_add_i32 s1, 0, 0x18800
	v_readlane_b32 s9, v246, 1
	v_lshrrev_b32_e32 v5, 5, v1
	s_add_u32 s22, s8, 0x60
	s_load_dwordx4 s[12:15], s[8:9], 0x90
	v_or_b32_e32 v4, 63, v1
	v_mul_u32_u24_e32 v13, 0x210, v5
	v_lshlrev_b32_e32 v6, 8, v5
	v_add_u32_e32 v5, 0x200, v1
	s_addc_u32 s23, s9, 0
	s_waitcnt lgkmcnt(0)
	s_lshr_b32 s0, s0, 16
	v_mul_u32_u24_e32 v9, 0x104, v4
	v_lshlrev_b32_e32 v4, 2, v1
	v_lshrrev_b32_e32 v5, 5, v5
	s_cmp_lg_u32 s0, 0
	v_add_u32_e32 v143, s1, v4
	v_mul_u32_u24_e32 v16, 0x210, v5
	v_lshlrev_b32_e32 v8, 8, v5
	v_add_u32_e32 v5, 0x600, v1
	s_cselect_b64 s[0:1], -1, 0
	v_mov_b32_e32 v99, 0
	v_lshrrev_b32_e32 v5, 5, v5
	s_cmp_lg_u64 s[0:1], 0
	v_mul_u32_u24_e32 v17, 0x210, v5
	v_lshlrev_b32_e32 v12, 8, v5
	s_addc_u32 s33, s11, 0
	s_sub_i32 s33, s33, 32
	v_lshl_add_u64 v[14:15], s[12:13], 0, v[98:99]
	s_mov_b64 s[0:1], 0x2000000
	v_mov_b32_e32 v5, v99
	v_or_b32_e32 v10, 0x2000, v6
	s_add_u32 s24, s14, 0xf000000
	v_lshl_add_u64 v[100:101], v[14:15], 0, s[0:1]
	v_lshl_add_u64 v[4:5], s[14:15], 0, v[4:5]
	s_mov_b64 s[0:1], 0x1eb68000
	s_mov_b32 s30, 0x6dc9c883
	s_mov_b32 s21, 0
	v_cmp_gt_u32_e64 s[6:7], 64, v1
	s_addc_u32 s25, s15, 0
	v_lshl_add_u64 v[102:103], v[4:5], 0, s[0:1]
	s_sub_i32 s36, s10, 32
	s_lshl_b32 s36, s36, 5
	s_lshl_b32 s37, s33, 5
	v_lshlrev_b32_e32 v104, 1, v2
	v_mov_b32_e32 v105, v99
	s_movk_i32 s38, 0x1400
	s_mov_b64 s[26:27], 0x4001000
	s_mov_b64 s[28:29], 0x400
	s_mov_b32 s31, 0x3fc45f30
	v_mov_b32_e32 v144, 0x358637bd
	s_mov_b32 s39, 0x800000
	v_add_u32_e32 v145, 0, v3
	v_add_u32_e32 v146, v7, v9
	v_add_u32_e32 v147, v11, v13
	v_lshlrev_b32_e32 v98, 1, v6
	v_add_u32_e32 v148, v11, v16
	v_lshlrev_b32_e32 v106, 1, v8
	v_lshlrev_b32_e32 v108, 1, v10
	v_add_u32_e32 v149, v11, v17
	v_lshlrev_b32_e32 v110, 1, v12
	s_sub_i32 s0, s10, 32
	v_mov_b64_e32 v[240:241], s[22:23]
	v_mov_b32_e32 v238, s18
	v_mov_b32_e32 v239, s19
	v_cndmask_b32_e64 v240, v238, v240, s[2:3]
	v_cndmask_b32_e64 v241, v239, v241, s[2:3]
	global_load_dwordx2 v[240:241], v[240:241], off
	s_waitcnt vmcnt(0)
	s_branch .LBB0_390

.LBB0_390:
	s_bfe_u32 s1, s0, 0x40003
	s_and_b32 s8, s36, 0xfffff000
	s_lshl_b32 s35, s1, 8
	s_or_b32 s40, s35, s8
	v_add_u32_e32 v2, s40, v140
	v_ashrrev_i32_e32 v3, 31, v2
	s_and_b32 s34, s0, 7
	v_lshlrev_b64 v[2:3], 11, v[2:3]
	v_lshl_add_u64 v[2:3], s[24:25], 0, v[2:3]
	s_lshl_b32 s20, s34, 7
	v_lshl_add_u64 v[2:3], v[2:3], 0, s[20:21]
	v_lshl_add_u64 v[18:19], v[2:3], 0, v[104:105]
	global_load_dwordx4 v[2:5], v[18:19], off offset:1024
	global_load_dwordx4 v[6:9], v[18:19], off offset:1040
	global_load_dwordx4 v[10:13], v[18:19], off offset:1056
	global_load_dwordx4 v[14:17], v[18:19], off offset:1072
	v_or_b32_sdwa v114, s40, v1 dst_sel:DWORD dst_unused:UNUSED_PAD src0_sel:DWORD src1_sel:BYTE_0
	v_ashrrev_i32_e32 v115, 31, v114
	s_and_saveexec_b64 s[8:9], s[2:3]
	s_xor_b64 s[8:9], exec, s[8:9]
	v_lshlrev_b64 v[238:239], 11, v[114:115]
	v_lshl_add_u64 v[238:239], s[98:99], 0, v[238:239]
	s_or_saveexec_b64 s[8:9], s[8:9]
	v_or_b32_e32 v116, s40, v1
	s_xor_b64 exec, exec, s[8:9]
	v_mov_b64_e32 v[238:239], s[14:15]
	v_mad_i64_i32 v[238:239], s[40:41], v116, s38, v[238:239]
	v_lshl_add_u64 v[238:239], v[238:239], 0, s[26:27]
	s_or_b64 exec, exec, s[8:9]
	s_lshl_b32 s8, s34, 6
	s_lshl_b32 s20, s8, 1
	v_lshl_add_u64 v[238:239], v[238:239], 0, s[20:21]
	global_load_dwordx4 v[82:85], v[238:239], off offset:48
	global_load_dwordx4 v[86:89], v[238:239], off offset:32
	global_load_dwordx4 v[90:93], v[238:239], off offset:16
	global_load_dwordx4 v[94:97], v[238:239], off
	global_load_dwordx4 v[66:69], v[238:239], off offset:112
	global_load_dwordx4 v[70:73], v[238:239], off offset:96
	global_load_dwordx4 v[74:77], v[238:239], off offset:80
	global_load_dwordx4 v[78:81], v[238:239], off offset:64
	s_waitcnt vmcnt(8)
	ds_write_b16 v141, v2
	ds_write_b16_d16_hi v141, v2 offset:528
	ds_write_b16 v141, v3 offset:1056
	ds_write_b16_d16_hi v141, v3 offset:1584
	ds_write_b16 v141, v4 offset:2112
	ds_write_b16_d16_hi v141, v4 offset:2640
	ds_write_b16 v141, v5 offset:3168
	ds_write_b16_d16_hi v141, v5 offset:3696
	ds_write_b16 v141, v6 offset:4224
	ds_write_b16_d16_hi v141, v6 offset:4752
	ds_write_b16 v141, v7 offset:5280
	ds_write_b16_d16_hi v141, v7 offset:5808
	ds_write_b16 v141, v8 offset:6336
	ds_write_b16_d16_hi v141, v8 offset:6864
	ds_write_b16 v141, v9 offset:7392
	ds_write_b16_d16_hi v141, v9 offset:7920
	ds_write_b16 v141, v10 offset:8448
	ds_write_b16_d16_hi v141, v10 offset:8976
	ds_write_b16 v141, v11 offset:9504
	ds_write_b16_d16_hi v141, v11 offset:10032
	ds_write_b16 v141, v12 offset:10560
	ds_write_b16_d16_hi v141, v12 offset:11088
	ds_write_b16 v141, v13 offset:11616
	ds_write_b16_d16_hi v141, v13 offset:12144
	ds_write_b16 v141, v14 offset:12672
	ds_write_b16_d16_hi v141, v14 offset:13200
	ds_write_b16 v141, v15 offset:13728
	ds_write_b16_d16_hi v141, v15 offset:14256
	ds_write_b16 v141, v16 offset:14784
	ds_write_b16_d16_hi v141, v16 offset:15312
	ds_write_b16 v141, v17 offset:15840
	ds_write_b16_d16_hi v141, v17 offset:16368
	s_waitcnt lgkmcnt(0)
	global_load_dwordx4 v[46:49], v[240:241], off offset:48
	global_load_dwordx4 v[54:57], v[240:241], off offset:32
	global_load_dwordx4 v[58:61], v[240:241], off offset:16
	global_load_dwordx4 v[62:65], v[240:241], off
	global_load_dwordx4 v[30:33], v[240:241], off offset:112
	global_load_dwordx4 v[38:41], v[240:241], off offset:96
	global_load_dwordx4 v[42:45], v[240:241], off offset:80
	global_load_dwordx4 v[50:53], v[240:241], off offset:64
	global_load_dwordx4 v[14:17], v[240:241], off offset:176
	global_load_dwordx4 v[22:25], v[240:241], off offset:160
	global_load_dwordx4 v[26:29], v[240:241], off offset:144
	global_load_dwordx4 v[34:37], v[240:241], off offset:128
	global_load_dwordx4 v[2:5], v[240:241], off offset:240
	global_load_dwordx4 v[6:9], v[240:241], off offset:224
	global_load_dwordx4 v[10:13], v[240:241], off offset:208
	global_load_dwordx4 v[18:21], v[240:241], off offset:192
	s_barrier
	s_and_saveexec_b64 s[8:9], s[2:3]
	s_xor_b64 s[8:9], exec, s[8:9]
	v_lshlrev_b64 v[112:113], 10, v[114:115]
	v_lshl_add_u64 v[112:113], s[12:13], 0, v[112:113]
	s_andn2_saveexec_b64 s[8:9], s[8:9]
	v_ashrrev_i32_e32 v117, 31, v116
	v_lshlrev_b64 v[112:113], 11, v[116:117]
	v_lshl_add_u64 v[112:113], s[24:25], 0, v[112:113]
	v_lshl_add_u64 v[112:113], v[112:113], 0, s[28:29]
	s_or_b64 exec, exec, s[8:9]
	v_or_b32_sdwa v107, s35, v1 dst_sel:DWORD dst_unused:UNUSED_PAD src0_sel:DWORD src1_sel:BYTE_0
	v_cvt_f64_u32_e32 v[114:115], v107
	v_cvt_f32_u32_e32 v109, v107
	v_mul_f64 v[116:117], v[114:115], s[30:31]
	v_rndne_f64_e32 v[116:117], v[116:117]
	v_fma_f64 v[114:115], v[114:115], s[30:31], -v[116:117]
	v_cvt_f32_f64_e32 v107, v[114:115]
	v_sin_f32_e32 v114, v107
	v_cos_f32_e32 v116, v107
	v_mul_f32_e32 v107, 0x3e4693af, v109
	v_cvt_f64_f32_e32 v[118:119], v107
	v_mul_f64 v[120:121], v[118:119], s[30:31]
	v_rndne_f64_e32 v[120:121], v[120:121]
	v_fma_f64 v[118:119], v[118:119], s[30:31], -v[120:121]
	s_waitcnt vmcnt(21)
	v_lshlrev_b32_e32 v122, 16, v90
	v_and_b32_e32 v123, 0xffff0000, v90
	v_mul_f32_e32 v90, 0x3d1a08c8, v109
	v_cvt_f32_f64_e32 v107, v[118:119]
	v_cvt_f64_f32_e32 v[118:119], v90
	v_mul_f64 v[120:121], v[118:119], s[30:31]
	v_rndne_f64_e32 v[120:121], v[120:121]
	v_fma_f64 v[118:119], v[118:119], s[30:31], -v[120:121]
	v_cvt_f32_f64_e32 v90, v[118:119]
	v_sin_f32_e32 v118, v90
	v_cos_f32_e32 v120, v90
	v_mul_f32_e32 v90, 0x3beef74e, v109
	v_cvt_f64_f32_e32 v[126:127], v90
	v_mul_f64 v[128:129], v[126:127], s[30:31]
	v_rndne_f64_e32 v[128:129], v[128:129]
	v_fma_f64 v[126:127], v[126:127], s[30:31], -v[128:129]
	v_cvt_f32_f64_e32 v90, v[126:127]
	v_sin_f32_e32 v119, v90
	v_cos_f32_e32 v121, v90
	v_mul_f32_e32 v90, 0x3ab95d22, v109
	v_lshlrev_b32_e32 v126, 16, v91
	v_and_b32_e32 v127, 0xffff0000, v91
	v_cvt_f64_f32_e32 v[90:91], v90
	s_waitcnt vmcnt(20)
	v_lshlrev_b32_e32 v124, 16, v94
	v_and_b32_e32 v125, 0xffff0000, v94
	v_lshlrev_b32_e32 v128, 16, v95
	v_and_b32_e32 v129, 0xffff0000, v95
	v_mul_f64 v[94:95], v[90:91], s[30:31]
	v_rndne_f64_e32 v[94:95], v[94:95]
	v_fma_f64 v[90:91], v[90:91], s[30:31], -v[94:95]
	v_cvt_f32_f64_e32 v91, v[90:91]
	v_sin_f32_e32 v90, v91
	v_cos_f32_e32 v94, v91
	v_mul_f32_e32 v91, 0x398fc8f8, v109
	v_cvt_f64_f32_e32 v[130:131], v91
	v_mul_f64 v[132:133], v[130:131], s[30:31]
	v_rndne_f64_e32 v[132:133], v[132:133]
	v_fma_f64 v[130:131], v[130:131], s[30:31], -v[132:133]
	v_cvt_f32_f64_e32 v95, v[130:131]
	v_lshlrev_b32_e32 v130, 16, v92
	v_and_b32_e32 v131, 0xffff0000, v92
	v_mul_f32_e32 v92, 0x385f10c5, v109
	v_cvt_f64_f32_e32 v[138:139], v92
	v_mul_f64 v[158:159], v[138:139], s[30:31]
	v_rndne_f64_e32 v[158:159], v[158:159]
	v_sin_f32_e32 v115, v107
	v_cos_f32_e32 v117, v107
	v_fma_f64 v[138:139], v[138:139], s[30:31], -v[158:159]
	v_mul_f32_e32 v107, 0x372d07a8, v109
	v_lshlrev_b32_e32 v132, 16, v96
	v_and_b32_e32 v133, 0xffff0000, v96
	v_cvt_f32_f64_e32 v96, v[138:139]
	v_cvt_f64_f32_e32 v[138:139], v107
	v_mul_f64 v[158:159], v[138:139], s[30:31]
	v_pk_mul_f32 v[136:137], v[124:125], v[124:125]
	v_rndne_f64_e32 v[158:159], v[158:159]
	v_pk_mul_f32 v[150:151], v[128:129], v[128:129]
	v_fma_f64 v[158:159], v[138:139], s[30:31], -v[158:159]
	v_lshlrev_b32_e32 v138, 16, v93
	v_and_b32_e32 v139, 0xffff0000, v93
	v_add_f32_e32 v93, v136, v137
	v_add_f32_e32 v93, v150, v93
	v_pk_mul_f32 v[154:155], v[132:133], v[132:133]
	v_add_f32_e32 v93, v151, v93
	v_lshlrev_b32_e32 v160, 16, v97
	v_and_b32_e32 v161, 0xffff0000, v97
	v_add_f32_e32 v93, v154, v93
	v_pk_mul_f32 v[162:163], v[160:161], v[160:161]
	v_add_f32_e32 v93, v155, v93
	v_add_f32_e32 v93, v162, v93
	v_pk_mul_f32 v[134:135], v[122:123], v[122:123]
	v_add_f32_e32 v93, v163, v93
	v_add_f32_e32 v93, v134, v93
	v_pk_mul_f32 v[152:153], v[126:127], v[126:127]
	v_add_f32_e32 v93, v135, v93
	v_add_f32_e32 v93, v152, v93
	v_pk_mul_f32 v[156:157], v[130:131], v[130:131]
	v_add_f32_e32 v93, v153, v93
	v_add_f32_e32 v93, v156, v93
	v_pk_mul_f32 v[164:165], v[138:139], v[138:139]
	v_add_f32_e32 v93, v157, v93
	v_lshlrev_b32_e32 v166, 16, v86
	v_and_b32_e32 v167, 0xffff0000, v86
	v_add_f32_e32 v93, v164, v93
	v_pk_mul_f32 v[168:169], v[166:167], v[166:167]
	v_add_f32_e32 v93, v165, v93
	v_lshlrev_b32_e32 v86, 16, v87
	v_and_b32_e32 v87, 0xffff0000, v87
	v_add_f32_e32 v93, v168, v93
	v_pk_mul_f32 v[170:171], v[86:87], v[86:87]
	v_add_f32_e32 v93, v169, v93
	v_lshlrev_b32_e32 v172, 16, v88
	v_and_b32_e32 v173, 0xffff0000, v88
	v_add_f32_e32 v93, v170, v93
	v_pk_mul_f32 v[174:175], v[172:173], v[172:173]
	v_add_f32_e32 v93, v171, v93
	v_lshlrev_b32_e32 v88, 16, v89
	v_and_b32_e32 v89, 0xffff0000, v89
	v_add_f32_e32 v93, v174, v93
	v_pk_mul_f32 v[176:177], v[88:89], v[88:89]
	v_add_f32_e32 v93, v175, v93
	v_lshlrev_b32_e32 v178, 16, v82
	v_and_b32_e32 v179, 0xffff0000, v82
	v_add_f32_e32 v93, v176, v93
	v_pk_mul_f32 v[180:181], v[178:179], v[178:179]
	v_add_f32_e32 v93, v177, v93
	v_lshlrev_b32_e32 v82, 16, v83
	v_and_b32_e32 v83, 0xffff0000, v83
	v_add_f32_e32 v93, v180, v93
	v_pk_mul_f32 v[182:183], v[82:83], v[82:83]
	v_add_f32_e32 v93, v181, v93
	v_lshlrev_b32_e32 v184, 16, v84
	v_and_b32_e32 v185, 0xffff0000, v84
	v_add_f32_e32 v93, v182, v93
	v_pk_mul_f32 v[186:187], v[184:185], v[184:185]
	v_add_f32_e32 v93, v183, v93
	v_lshlrev_b32_e32 v84, 16, v85
	v_and_b32_e32 v85, 0xffff0000, v85
	v_add_f32_e32 v93, v186, v93
	v_pk_mul_f32 v[188:189], v[84:85], v[84:85]
	v_add_f32_e32 v93, v187, v93
	s_waitcnt vmcnt(16)
	v_lshlrev_b32_e32 v190, 16, v78
	v_and_b32_e32 v191, 0xffff0000, v78
	v_add_f32_e32 v93, v188, v93
	v_pk_mul_f32 v[192:193], v[190:191], v[190:191]
	v_add_f32_e32 v93, v189, v93
	v_lshlrev_b32_e32 v78, 16, v79
	v_and_b32_e32 v79, 0xffff0000, v79
	v_add_f32_e32 v93, v192, v93
	v_pk_mul_f32 v[194:195], v[78:79], v[78:79]
	v_add_f32_e32 v93, v193, v93
	v_lshlrev_b32_e32 v196, 16, v80
	v_and_b32_e32 v197, 0xffff0000, v80
	v_add_f32_e32 v93, v194, v93
	v_pk_mul_f32 v[198:199], v[196:197], v[196:197]
	v_add_f32_e32 v93, v195, v93
	v_lshlrev_b32_e32 v80, 16, v81
	v_and_b32_e32 v81, 0xffff0000, v81
	v_add_f32_e32 v93, v198, v93
	v_pk_mul_f32 v[200:201], v[80:81], v[80:81]
	v_add_f32_e32 v93, v199, v93
	v_lshlrev_b32_e32 v202, 16, v74
	v_and_b32_e32 v203, 0xffff0000, v74
	v_add_f32_e32 v93, v200, v93
	v_pk_mul_f32 v[204:205], v[202:203], v[202:203]
	v_add_f32_e32 v93, v201, v93
	v_lshlrev_b32_e32 v74, 16, v75
	v_and_b32_e32 v75, 0xffff0000, v75
	v_add_f32_e32 v93, v204, v93
	v_pk_mul_f32 v[206:207], v[74:75], v[74:75]
	v_add_f32_e32 v93, v205, v93
	v_lshlrev_b32_e32 v208, 16, v76
	v_and_b32_e32 v209, 0xffff0000, v76
	v_add_f32_e32 v93, v206, v93
	v_pk_mul_f32 v[210:211], v[208:209], v[208:209]
	v_add_f32_e32 v93, v207, v93
	v_lshlrev_b32_e32 v76, 16, v77
	v_and_b32_e32 v77, 0xffff0000, v77
	v_add_f32_e32 v93, v210, v93
	v_pk_mul_f32 v[212:213], v[76:77], v[76:77]
	v_add_f32_e32 v93, v211, v93
	v_lshlrev_b32_e32 v214, 16, v70
	v_and_b32_e32 v215, 0xffff0000, v70
	v_add_f32_e32 v93, v212, v93
	v_pk_mul_f32 v[216:217], v[214:215], v[214:215]
	v_add_f32_e32 v93, v213, v93
	v_lshlrev_b32_e32 v70, 16, v71
	v_and_b32_e32 v71, 0xffff0000, v71
	v_add_f32_e32 v93, v216, v93
	v_pk_mul_f32 v[218:219], v[70:71], v[70:71]
	v_add_f32_e32 v93, v217, v93
	v_lshlrev_b32_e32 v220, 16, v72
	v_and_b32_e32 v221, 0xffff0000, v72
	v_add_f32_e32 v93, v218, v93
	v_pk_mul_f32 v[222:223], v[220:221], v[220:221]
	v_add_f32_e32 v93, v219, v93
	v_lshlrev_b32_e32 v72, 16, v73
	v_and_b32_e32 v73, 0xffff0000, v73
	v_add_f32_e32 v93, v222, v93
	v_pk_mul_f32 v[224:225], v[72:73], v[72:73]
	v_add_f32_e32 v93, v223, v93
	v_lshlrev_b32_e32 v226, 16, v66
	v_and_b32_e32 v227, 0xffff0000, v66
	v_add_f32_e32 v93, v224, v93
	v_pk_mul_f32 v[228:229], v[226:227], v[226:227]
	v_add_f32_e32 v93, v225, v93
	v_lshlrev_b32_e32 v66, 16, v67
	v_and_b32_e32 v67, 0xffff0000, v67
	v_add_f32_e32 v93, v228, v93
	v_pk_mul_f32 v[230:231], v[66:67], v[66:67]
	v_add_f32_e32 v93, v229, v93
	v_lshlrev_b32_e32 v232, 16, v68
	v_and_b32_e32 v233, 0xffff0000, v68
	v_add_f32_e32 v93, v230, v93
	v_pk_mul_f32 v[234:235], v[232:233], v[232:233]
	v_add_f32_e32 v93, v231, v93
	v_lshlrev_b32_e32 v68, 16, v69
	v_and_b32_e32 v69, 0xffff0000, v69
	v_add_f32_e32 v93, v234, v93
	v_pk_mul_f32 v[236:237], v[68:69], v[68:69]
	v_add_f32_e32 v93, v235, v93
	v_add_f32_e32 v93, v236, v93
	v_add_f32_e32 v93, v237, v93
	v_fmamk_f32 v93, v93, 0x3c800000, v144
	v_mul_f32_e32 v97, 0x4b800000, v93
	v_cmp_gt_f32_e64 s[8:9], s39, v93
	v_sin_f32_e32 v91, v95
	v_sin_f32_e32 v92, v96
	v_cndmask_b32_e64 v93, v93, v97, s[8:9]
	v_rsq_f32_e32 v107, v93
	v_cvt_f32_f64_e32 v97, v[158:159]
	v_sin_f32_e32 v93, v97
	v_cos_f32_e32 v95, v95
	v_mul_f32_e32 v109, 0x45800000, v107
	v_cndmask_b32_e64 v134, v107, v109, s[8:9]
	v_pk_mul_f32 v[124:125], v[134:135], v[124:125] op_sel_hi:[0,1]
	s_waitcnt vmcnt(12)
	v_pk_mul_f32 v[62:63], v[62:63], v[124:125]
	v_pk_mul_f32 v[124:125], v[134:135], v[128:129] op_sel_hi:[0,1]
	v_pk_mul_f32 v[64:65], v[64:65], v[124:125]
	v_pk_mul_f32 v[124:125], v[134:135], v[132:133] op_sel_hi:[0,1]
	v_pk_mul_f32 v[58:59], v[58:59], v[124:125]
	v_pk_mul_f32 v[124:125], v[134:135], v[160:161] op_sel_hi:[0,1]
	v_pk_mul_f32 v[124:125], v[60:61], v[124:125]
	v_pk_mul_f32 v[60:61], v[134:135], v[122:123] op_sel_hi:[0,1]
	v_pk_mul_f32 v[54:55], v[54:55], v[60:61]
	v_pk_mul_f32 v[60:61], v[134:135], v[126:127] op_sel_hi:[0,1]
	v_pk_mul_f32 v[60:61], v[56:57], v[60:61]
	v_pk_mul_f32 v[56:57], v[134:135], v[130:131] op_sel_hi:[0,1]
	v_pk_mul_f32 v[122:123], v[46:47], v[56:57]
	v_pk_mul_f32 v[46:47], v[134:135], v[138:139] op_sel_hi:[0,1]
	v_pk_mul_f32 v[126:127], v[48:49], v[46:47]
	v_pk_mul_f32 v[46:47], v[134:135], v[166:167] op_sel_hi:[0,1]
	s_waitcnt vmcnt(8)
	v_pk_mul_f32 v[46:47], v[50:51], v[46:47]
	v_pk_mul_f32 v[50:51], v[134:135], v[172:173] op_sel_hi:[0,1]
	v_pk_mul_f32 v[42:43], v[42:43], v[50:51]
	v_pk_mul_f32 v[50:51], v[134:135], v[88:89] op_sel_hi:[0,1]
	v_pk_mul_f32 v[44:45], v[44:45], v[50:51]
	v_pk_mul_f32 v[50:51], v[134:135], v[178:179] op_sel_hi:[0,1]
	v_pk_mul_f32 v[38:39], v[38:39], v[50:51]
	v_pk_mul_f32 v[50:51], v[134:135], v[82:83] op_sel_hi:[0,1]
	v_pk_mul_f32 v[40:41], v[40:41], v[50:51]
	v_pk_mul_f32 v[50:51], v[134:135], v[184:185] op_sel_hi:[0,1]
	v_pk_mul_f32 v[30:31], v[30:31], v[50:51]
	v_pk_mul_f32 v[50:51], v[134:135], v[84:85] op_sel_hi:[0,1]
	v_pk_mul_f32 v[32:33], v[32:33], v[50:51]
	v_pk_mul_f32 v[50:51], v[134:135], v[190:191] op_sel_hi:[0,1]
	s_waitcnt vmcnt(4)
	v_pk_mul_f32 v[34:35], v[34:35], v[50:51]
	v_pk_mul_f32 v[50:51], v[134:135], v[78:79] op_sel_hi:[0,1]
	v_pk_mul_f32 v[36:37], v[36:37], v[50:51]
	v_pk_mul_f32 v[50:51], v[134:135], v[196:197] op_sel_hi:[0,1]
	v_pk_mul_f32 v[26:27], v[26:27], v[50:51]
	v_pk_mul_f32 v[50:51], v[134:135], v[80:81] op_sel_hi:[0,1]
	v_pk_mul_f32 v[28:29], v[28:29], v[50:51]
	v_pk_mul_f32 v[50:51], v[134:135], v[202:203] op_sel_hi:[0,1]
	v_pk_mul_f32 v[22:23], v[22:23], v[50:51]
	v_pk_mul_f32 v[50:51], v[134:135], v[74:75] op_sel_hi:[0,1]
	v_pk_mul_f32 v[24:25], v[24:25], v[50:51]
	v_pk_mul_f32 v[50:51], v[134:135], v[208:209] op_sel_hi:[0,1]
	v_pk_mul_f32 v[14:15], v[14:15], v[50:51]
	v_pk_mul_f32 v[50:51], v[134:135], v[76:77] op_sel_hi:[0,1]
	v_pk_mul_f32 v[16:17], v[16:17], v[50:51]
	v_pk_mul_f32 v[50:51], v[134:135], v[214:215] op_sel_hi:[0,1]
	s_waitcnt vmcnt(0)
	v_pk_mul_f32 v[18:19], v[18:19], v[50:51]
	v_pk_mul_f32 v[50:51], v[134:135], v[70:71] op_sel_hi:[0,1]
	v_pk_mul_f32 v[20:21], v[20:21], v[50:51]
	v_pk_mul_f32 v[50:51], v[134:135], v[220:221] op_sel_hi:[0,1]
	v_pk_mul_f32 v[10:11], v[10:11], v[50:51]
	v_pk_mul_f32 v[50:51], v[134:135], v[72:73] op_sel_hi:[0,1]
	v_pk_mul_f32 v[12:13], v[12:13], v[50:51]
	v_pk_mul_f32 v[50:51], v[134:135], v[226:227] op_sel_hi:[0,1]
	v_pk_mul_f32 v[6:7], v[6:7], v[50:51]
	v_pk_mul_f32 v[50:51], v[134:135], v[66:67] op_sel_hi:[0,1]
	v_pk_mul_f32 v[8:9], v[8:9], v[50:51]
	v_pk_mul_f32 v[50:51], v[134:135], v[232:233] op_sel_hi:[0,1]
	v_pk_mul_f32 v[2:3], v[2:3], v[50:51]
	v_pk_mul_f32 v[50:51], v[134:135], v[68:69] op_sel_hi:[0,1]
	v_pk_mul_f32 v[48:49], v[134:135], v[86:87] op_sel_hi:[0,1]
	v_pk_mul_f32 v[4:5], v[4:5], v[50:51]
	v_pk_mul_f32 v[50:51], v[114:115], v[54:55]
	v_cos_f32_e32 v96, v96
	v_cos_f32_e32 v97, v97
	v_pk_mul_f32 v[48:49], v[52:53], v[48:49]
	v_pk_fma_f32 v[52:53], v[116:117], v[62:63], v[50:51] neg_lo:[0,0,1] neg_hi:[0,0,1]
	v_pk_mul_f32 v[50:51], v[114:115], v[62:63]
	v_pk_mul_f32 v[62:63], v[92:93], v[126:127]
	v_pk_fma_f32 v[50:51], v[116:117], v[54:55], v[50:51]
	v_pk_mul_f32 v[54:55], v[118:119], v[60:61]
	v_lshl_add_u64 v[70:71], v[112:113], 0, s[20:21]
	v_pk_fma_f32 v[56:57], v[120:121], v[64:65], v[54:55] neg_lo:[0,0,1] neg_hi:[0,0,1]
	v_pk_mul_f32 v[54:55], v[118:119], v[64:65]
	v_pk_fma_f32 v[64:65], v[96:97], v[124:125], v[62:63] neg_lo:[0,0,1] neg_hi:[0,0,1]
	v_pk_fma_f32 v[54:55], v[120:121], v[60:61], v[54:55]
	v_pk_mul_f32 v[60:61], v[90:91], v[122:123]
	v_pk_mul_f32 v[62:63], v[92:93], v[124:125]
	v_pk_fma_f32 v[60:61], v[94:95], v[58:59], v[60:61] neg_lo:[0,0,1] neg_hi:[0,0,1]
	v_pk_mul_f32 v[58:59], v[90:91], v[58:59]
	v_pk_fma_f32 v[62:63], v[96:97], v[126:127], v[62:63]
	v_pk_fma_f32 v[58:59], v[94:95], v[122:123], v[58:59]
	v_cvt_pk_bf16_f32 v66, v52, v53
	v_cvt_pk_bf16_f32 v67, v56, v57
	v_cvt_pk_bf16_f32 v68, v60, v61
	v_cvt_pk_bf16_f32 v69, v64, v65
	global_store_dwordx4 v[70:71], v[66:69], off
	s_nop 1
	v_cvt_pk_bf16_f32 v66, v50, v51
	v_cvt_pk_bf16_f32 v67, v54, v55
	v_cvt_pk_bf16_f32 v68, v58, v59
	v_cvt_pk_bf16_f32 v69, v62, v63
	global_store_dwordx4 v[70:71], v[66:69], off offset:16
	s_nop 1
	v_cvt_pk_bf16_f32 v66, v46, v47
	v_cvt_pk_bf16_f32 v67, v48, v49
	v_cvt_pk_bf16_f32 v68, v42, v43
	v_cvt_pk_bf16_f32 v69, v44, v45
	global_store_dwordx4 v[70:71], v[66:69], off offset:32
	s_nop 1
	v_cvt_pk_bf16_f32 v66, v38, v39
	v_cvt_pk_bf16_f32 v67, v40, v41
	v_cvt_pk_bf16_f32 v68, v30, v31
	v_cvt_pk_bf16_f32 v69, v32, v33
	global_store_dwordx4 v[70:71], v[66:69], off offset:48
	s_nop 1
	v_cvt_pk_bf16_f32 v66, v34, v35
	v_cvt_pk_bf16_f32 v67, v36, v37
	v_cvt_pk_bf16_f32 v68, v26, v27
	v_cvt_pk_bf16_f32 v69, v28, v29
	global_store_dwordx4 v[70:71], v[66:69], off offset:64
	s_nop 1
	v_cvt_pk_bf16_f32 v66, v22, v23
	v_cvt_pk_bf16_f32 v67, v24, v25
	v_cvt_pk_bf16_f32 v68, v14, v15
	v_cvt_pk_bf16_f32 v69, v16, v17
	global_store_dwordx4 v[70:71], v[66:69], off offset:80
	s_nop 1
	v_cvt_pk_bf16_f32 v66, v18, v19
	v_cvt_pk_bf16_f32 v67, v20, v21
	v_cvt_pk_bf16_f32 v68, v10, v11
	v_cvt_pk_bf16_f32 v69, v12, v13
	global_store_dwordx4 v[70:71], v[66:69], off offset:96
	s_nop 1
	v_cvt_pk_bf16_f32 v66, v6, v7
	v_cvt_pk_bf16_f32 v67, v8, v9
	v_cvt_pk_bf16_f32 v68, v2, v3
	v_cvt_pk_bf16_f32 v69, v4, v5
	global_store_dwordx4 v[70:71], v[66:69], off offset:112
	s_and_saveexec_b64 s[8:9], s[4:5]
	s_cbranch_execz .LBB0_400
	ds_write2_b32 v145, v52, v53 offset1:1
	ds_write2_b32 v145, v56, v57 offset0:2 offset1:3
	ds_write2_b32 v145, v60, v61 offset0:4 offset1:5
	ds_write2_b32 v145, v64, v65 offset0:6 offset1:7
	ds_write2_b32 v145, v50, v51 offset0:8 offset1:9
	ds_write2_b32 v145, v54, v55 offset0:10 offset1:11
	ds_write2_b32 v145, v58, v59 offset0:12 offset1:13
	ds_write2_b32 v145, v62, v63 offset0:14 offset1:15
	ds_write2_b32 v145, v46, v47 offset0:16 offset1:17
	ds_write2_b32 v145, v48, v49 offset0:18 offset1:19
	ds_write2_b32 v145, v42, v43 offset0:20 offset1:21
	ds_write2_b32 v145, v44, v45 offset0:22 offset1:23
	ds_write2_b32 v145, v38, v39 offset0:24 offset1:25
	ds_write2_b32 v145, v40, v41 offset0:26 offset1:27
	ds_write2_b32 v145, v30, v31 offset0:28 offset1:29
	ds_write2_b32 v145, v32, v33 offset0:30 offset1:31
	ds_write2_b32 v145, v34, v35 offset0:32 offset1:33
	ds_write2_b32 v145, v36, v37 offset0:34 offset1:35
	ds_write2_b32 v145, v26, v27 offset0:36 offset1:37
	ds_write2_b32 v145, v28, v29 offset0:38 offset1:39
	ds_write2_b32 v145, v22, v23 offset0:40 offset1:41
	ds_write2_b32 v145, v24, v25 offset0:42 offset1:43
	ds_write2_b32 v145, v14, v15 offset0:44 offset1:45
	ds_write2_b32 v145, v16, v17 offset0:46 offset1:47
	ds_write2_b32 v145, v18, v19 offset0:48 offset1:49
	ds_write2_b32 v145, v20, v21 offset0:50 offset1:51
	ds_write2_b32 v145, v10, v11 offset0:52 offset1:53
	ds_write2_b32 v145, v12, v13 offset0:54 offset1:55
	ds_write2_b32 v145, v6, v7 offset0:56 offset1:57
	ds_write2_b32 v145, v8, v9 offset0:58 offset1:59
	ds_write2_b32 v145, v2, v3 offset0:60 offset1:61
	ds_write2_b32 v145, v4, v5 offset0:62 offset1:63
